# attention younger half: QK does key block 0 first, its softmax in the gaps of the key block 1 MFMAs, first V fragments read at the end of QK
# baseline (speedup 1.0000x reference)
; #define ATT_WAIT(n) asm volatile("s_waitcnt vmcnt(" #n ")" ::: "memory")
; #define ATT_BAR() do { asm volatile("s_waitcnt lgkmcnt(0)" ::: "memory"); __builtin_amdgcn_s_barrier(); asm volatile("" ::: "memory"); } while (0)
; #define ATT_ISSUE_K() attn_issue_k(F, KH + (size_t)ATT_TILE((t + 2 < nt) ? t + 2 : nt - 1) * ATT_KB, lds + b2 * ATT_KB)
; __device__ __forceinline__ void attn_unit(const Frame& F, int h, int qb, const float* qw, bool desc) {
;     ...
;         for (int t = 0; t < nt; ++t) {
;             const int tl = ATT_TILE(t), tlp = ATT_TILE(t - 1);
;             ATT_ISSUE_K(); if (t > 0) { ATT_SMPV(tlp, bp); } ATT_WAIT(8); ATT_BAR();
.LBB0_1006:
	s_setprio 0
	s_min_u32 s89, s72, s45
	s_mul_i32 s0, s89, 0x6000
	s_add_u32 s92, s40, s0
	s_addc_u32 s93, s41, 0
	s_mul_i32 s0, s75, 0x6000
	v_mov_b32_e32 v2, v164
	s_add_i32 s0, s0, 0
	s_add_i32 m0, s0, s56
	s_add_u32 s98, s92, s8
	s_addc_u32 s99, s93, s9
	global_load_lds_dwordx4 v164, s[98:99]
	s_add_u32 s100, s92, s10
	s_addc_u32 s101, s93, s11
	s_add_i32 m0, s0, s57
	s_add_u32 s98, s92, s12
	s_addc_u32 s99, s93, s13
	global_load_lds_dwordx4 v164, s[100:101]
	s_add_i32 m0, s0, s58
	s_cmp_eq_u32 s74, 0
	global_load_lds_dwordx4 v164, s[98:99]
	s_mov_b32 s0, s91
	s_cbranch_scc1 .LBB0_1012
	s_sub_i32 s91, s74, 64
	s_cmp_gt_i32 s91, s70
	s_cbranch_scc1 .LBB0_1011
	s_cmp_le_i32 s74, s1
	s_cbranch_scc1 .LBB0_1010
	v_cmp_lt_i32_e32 vcc, 31, v184
	s_nop 1
	v_cndmask_b32_e32 v82, v167, v82, vcc
	v_cmp_lt_i32_e32 vcc, 32, v184
	s_nop 1
	v_cndmask_b32_e32 v83, v167, v83, vcc
	v_cmp_lt_i32_e32 vcc, 33, v184
	s_nop 1
	v_cndmask_b32_e32 v84, v167, v84, vcc
	v_cmp_lt_i32_e32 vcc, 34, v184
	s_nop 1
	v_cndmask_b32_e32 v85, v167, v85, vcc
	v_cmp_lt_i32_e32 vcc, 39, v184
	s_nop 1
	v_cndmask_b32_e32 v86, v167, v86, vcc
	v_cmp_lt_i32_e32 vcc, 40, v184
	s_nop 1
	v_cndmask_b32_e32 v87, v167, v87, vcc
	v_cmp_lt_i32_e32 vcc, 41, v184
	s_nop 1
	v_cndmask_b32_e32 v88, v167, v88, vcc
	v_cmp_lt_i32_e32 vcc, 42, v184
	s_nop 1
	v_cndmask_b32_e32 v89, v167, v89, vcc
	v_cmp_lt_i32_e32 vcc, 47, v184
	s_nop 1
	v_cndmask_b32_e32 v90, v167, v90, vcc
	v_cmp_lt_i32_e32 vcc, 48, v184
	s_nop 1
	v_cndmask_b32_e32 v91, v167, v91, vcc
	v_cmp_lt_i32_e32 vcc, 49, v184
	s_nop 1
	v_cndmask_b32_e32 v92, v167, v92, vcc
	v_cmp_lt_i32_e32 vcc, 50, v184
	s_nop 1
	v_cndmask_b32_e32 v93, v167, v93, vcc
	v_cmp_lt_i32_e32 vcc, 55, v184
	s_nop 1
	v_cndmask_b32_e32 v94, v167, v94, vcc
	v_cmp_lt_i32_e32 vcc, 56, v184
	s_nop 1
	v_cndmask_b32_e32 v95, v167, v95, vcc
	v_cmp_lt_i32_e32 vcc, 57, v184
	s_nop 1
	v_cndmask_b32_e32 v96, v167, v96, vcc
	v_cmp_lt_i32_e32 vcc, 58, v184
	s_nop 1
	v_cndmask_b32_e32 v97, v167, v97, vcc
.LBB0_1010:
	s_lshl_b32 s90, s90, 14
	s_add_i32 s90, s90, 0x12000
	s_setprio 2
	s_waitcnt lgkmcnt(7)
	v_mfma_f32_32x32x16_bf16 v[66:81], v[222:225], v[4:7], v[66:81]
	v_exp_f32_e32 v2, v82
	v_exp_f32_e32 v185, v83
	s_nop 0
	v_add_f32_e32 v205, v2, v17
	s_waitcnt lgkmcnt(6)
	v_mfma_f32_32x32x16_bf16 v[50:65], v[226:229], v[4:7], v[50:65]
	v_exp_f32_e32 v198, v84
	v_exp_f32_e32 v16, v85
	s_waitcnt lgkmcnt(5)
	v_mfma_f32_32x32x16_bf16 v[34:49], v[230:233], v[4:7], v[34:49]
	v_exp_f32_e32 v17, v86
	v_exp_f32_e32 v199, v87
	s_waitcnt lgkmcnt(4)
	v_mfma_f32_32x32x16_bf16 v[18:33], v[234:237], v[4:7], v[18:33]
	v_exp_f32_e32 v202, v88
	v_exp_f32_e32 v200, v89
	v_add_u32_e32 v82, s90, v172
	ds_read_b128 v[4:7], v82
	ds_read_b128 v[8:11], v82 offset:4096
	ds_read_b128 v[12:15], v82 offset:8192
	ds_read_b128 v[82:85], v82 offset:12288
	s_waitcnt lgkmcnt(7)
	v_mfma_f32_32x32x16_bf16 v[66:81], v[238:241], v[106:109], v[66:81]
	v_exp_f32_e32 v201, v90
	v_exp_f32_e32 v203, v91
	s_waitcnt lgkmcnt(6)
	v_mfma_f32_32x32x16_bf16 v[50:65], v[242:245], v[106:109], v[50:65]
	v_exp_f32_e32 v206, v92
	v_exp_f32_e32 v204, v93
	s_waitcnt lgkmcnt(5)
	v_mfma_f32_32x32x16_bf16 v[34:49], v[246:249], v[106:109], v[34:49]
	v_exp_f32_e32 v186, v94
	v_exp_f32_e32 v187, v95
	s_waitcnt lgkmcnt(4)
	v_mfma_f32_32x32x16_bf16 v[18:33], v[250:253], v[106:109], v[18:33]
	v_exp_f32_e32 v112, v96
	v_exp_f32_e32 v110, v97
	v_add_u32_e32 v98, s90, v173
	ds_read_b128 v[86:89], v98
	ds_read_b128 v[90:93], v98 offset:4096
	ds_read_b128 v[94:97], v98 offset:8192
	ds_read_b128 v[98:101], v98 offset:12288
	v_cvt_pk_bf16_f32 v102, v2, v185
	v_cvt_pk_bf16_f32 v103, v198, v16
	v_cvt_pk_bf16_f32 v104, v17, v199
	v_cvt_pk_bf16_f32 v105, v202, v200
	v_cvt_pk_bf16_f32 v106, v201, v203
	v_cvt_pk_bf16_f32 v107, v206, v204
	v_cvt_pk_bf16_f32 v108, v186, v187
	v_cvt_pk_bf16_f32 v109, v112, v110
	s_waitcnt lgkmcnt(7)
	v_mfma_f32_32x32x16_bf16 v[66:81], v[4:7], v[102:105], v[66:81]
	v_add_f32_e32 v185, v185, v198
	v_add_f32_e32 v16, v16, v17
	s_waitcnt lgkmcnt(6)
	v_mfma_f32_32x32x16_bf16 v[50:65], v[8:11], v[102:105], v[50:65]
	v_add_f32_e32 v199, v199, v202
	v_add_f32_e32 v200, v200, v201
	s_waitcnt lgkmcnt(5)
	v_mfma_f32_32x32x16_bf16 v[34:49], v[12:15], v[102:105], v[34:49]
	v_add_f32_e32 v203, v203, v206
	v_add_f32_e32 v204, v204, v186
	s_waitcnt lgkmcnt(4)
	v_mfma_f32_32x32x16_bf16 v[18:33], v[82:85], v[102:105], v[18:33]
	v_add_f32_e32 v187, v187, v112
	v_add_f32_e32 v205, v205, v110
	s_waitcnt lgkmcnt(0)
	v_mfma_f32_32x32x16_bf16 v[66:81], v[86:89], v[106:109], v[66:81]
	v_add_f32_e32 v185, v185, v16
	v_add_f32_e32 v199, v199, v200
	v_mfma_f32_32x32x16_bf16 v[50:65], v[90:93], v[106:109], v[50:65]
	v_add_f32_e32 v203, v203, v204
	v_add_f32_e32 v187, v187, v205
	v_mfma_f32_32x32x16_bf16 v[34:49], v[94:97], v[106:109], v[34:49]
	v_add_f32_e32 v185, v185, v199
	v_add_f32_e32 v203, v203, v187
	v_mfma_f32_32x32x16_bf16 v[18:33], v[98:101], v[106:109], v[18:33]
	v_add_f32_e32 v185, v185, v203
	v_add_f32_e32 v178, v178, v185

.LBB0_1013:
	s_lshl_b32 s89, s89, 14
	s_add_u32 s92, s42, s89
	s_addc_u32 s93, s43, 0
	s_lshl_b32 s89, s75, 14
	s_add_i32 s89, s89, 0x12000
	s_add_i32 vcc_lo, s89, s59
	s_add_i32 vcc_hi, s89, s60
	s_add_u32 s98, s92, s14
	s_addc_u32 s99, s93, s15
	s_add_u32 s100, s92, s16
	s_addc_u32 s101, s93, s17
	s_mul_i32 s89, s0, 0x6000
	v_add_u32_e32 v2, s89, v174
	v_add_u32_e32 v16, s89, v175
	v_add_u32_e32 v17, s89, v176
	v_add_u32_e32 v185, s89, v177
	ds_read_b128 v[4:7], v2
	ds_read_b128 v[8:11], v16
	ds_read_b128 v[12:15], v17
	ds_read_b128 v[186:189], v185
	ds_read_b128 v[190:193], v2 offset:128
	ds_read_b128 v[194:197], v16 offset:128
	ds_read_b128 v[198:201], v17 offset:128
	ds_read_b128 v[202:205], v185 offset:128
	s_waitcnt vmcnt(8)
	s_waitcnt lgkmcnt(0)
	s_barrier
	s_setprio 1
	s_cmp_gt_i32 s90, s70
	s_cbranch_scc1 .Lmy_attn_skipqk_b
	v_mfma_f32_32x32x16_bf16 v[98:113], v[4:7], v[114:117], 0
	v_mfma_f32_32x32x16_bf16 v[98:113], v[8:11], v[118:121], v[98:113]
	ds_read_b128 v[206:209], v2 offset:256
	ds_read_b128 v[210:213], v16 offset:256
	ds_read_b128 v[214:217], v17 offset:256
	ds_read_b128 v[218:221], v185 offset:256
	v_mfma_f32_32x32x16_bf16 v[98:113], v[12:15], v[122:125], v[98:113]
	s_mov_b32 m0, vcc_lo
	s_nop 0
	global_load_lds_dwordx4 v164, s[98:99]
	v_mfma_f32_32x32x16_bf16 v[98:113], v[186:189], v[126:129], v[98:113]
	s_mov_b32 m0, vcc_hi
	s_nop 0
	global_load_lds_dwordx4 v164, s[100:101]
	ds_read_b128 v[4:7], v2 offset:12288
	ds_read_b128 v[8:11], v16 offset:12288
	ds_read_b128 v[12:15], v17 offset:12288
	ds_read_b128 v[186:189], v185 offset:12288
	s_waitcnt lgkmcnt(8)
	v_mfma_f32_32x32x16_bf16 v[98:113], v[190:193], v[130:133], v[98:113]
	v_mfma_f32_32x32x16_bf16 v[98:113], v[194:197], v[134:137], v[98:113]
	v_mfma_f32_32x32x16_bf16 v[98:113], v[198:201], v[138:141], v[98:113]
	v_mfma_f32_32x32x16_bf16 v[98:113], v[202:205], v[142:145], v[98:113]
	ds_read_b128 v[190:193], v2 offset:12416
	ds_read_b128 v[194:197], v16 offset:12416
	ds_read_b128 v[198:201], v17 offset:12416
	ds_read_b128 v[202:205], v185 offset:12416
	s_waitcnt lgkmcnt(8)
	v_mfma_f32_32x32x16_bf16 v[98:113], v[206:209], v[146:149], v[98:113]
	v_mfma_f32_32x32x16_bf16 v[98:113], v[210:213], v[154:157], v[98:113]
	v_mfma_f32_32x32x16_bf16 v[98:113], v[214:217], v[150:153], v[98:113]
	v_mfma_f32_32x32x16_bf16 v[98:113], v[218:221], v[158:161], v[98:113]
	ds_read_b128 v[206:209], v2 offset:12544
	ds_read_b128 v[210:213], v16 offset:12544
	ds_read_b128 v[214:217], v17 offset:12544
	ds_read_b128 v[218:221], v185 offset:12544
	s_waitcnt lgkmcnt(8)
	v_mfma_f32_32x32x16_bf16 v[82:97], v[4:7], v[114:117], 0
	v_mfma_f32_32x32x16_bf16 v[82:97], v[8:11], v[118:121], v[82:97]
	v_mfma_f32_32x32x16_bf16 v[82:97], v[12:15], v[122:125], v[82:97]
	v_mfma_f32_32x32x16_bf16 v[82:97], v[186:189], v[126:129], v[82:97]
	s_nop 3
	s_add_i32 s89, s74, 64
	s_cmp_le_i32 s89, s1
	s_cbranch_scc1 .Lmy_b_nomask0
	v_subrev_u32_e32 v2, 64, v184
	v_cmp_lt_i32_e32 vcc, -1, v2
	s_nop 1
	v_cndmask_b32_e32 v98, v167, v98, vcc
	v_cmp_lt_i32_e32 vcc, 0, v2
	s_nop 1
	v_cndmask_b32_e32 v99, v167, v99, vcc
	v_cmp_lt_i32_e32 vcc, 1, v2
	s_nop 1
	v_cndmask_b32_e32 v100, v167, v100, vcc
	v_cmp_lt_i32_e32 vcc, 2, v2
	s_nop 1
	v_cndmask_b32_e32 v101, v167, v101, vcc
	v_cmp_lt_i32_e32 vcc, 7, v2
	s_nop 1
	v_cndmask_b32_e32 v102, v167, v102, vcc
	v_cmp_lt_i32_e32 vcc, 8, v2
	s_nop 1
	v_cndmask_b32_e32 v103, v167, v103, vcc
	v_cmp_lt_i32_e32 vcc, 9, v2
	s_nop 1
	v_cndmask_b32_e32 v104, v167, v104, vcc
	v_cmp_lt_i32_e32 vcc, 10, v2
	s_nop 1
	v_cndmask_b32_e32 v105, v167, v105, vcc
	v_cmp_lt_i32_e32 vcc, 15, v2
	s_nop 1
	v_cndmask_b32_e32 v106, v167, v106, vcc
	v_cmp_lt_i32_e32 vcc, 16, v2
	s_nop 1
	v_cndmask_b32_e32 v107, v167, v107, vcc
	v_cmp_lt_i32_e32 vcc, 17, v2
	s_nop 1
	v_cndmask_b32_e32 v108, v167, v108, vcc
	v_cmp_lt_i32_e32 vcc, 18, v2
	s_nop 1
	v_cndmask_b32_e32 v109, v167, v109, vcc
	v_cmp_lt_i32_e32 vcc, 23, v2
	s_nop 1
	v_cndmask_b32_e32 v110, v167, v110, vcc
	v_cmp_lt_i32_e32 vcc, 24, v2
	s_nop 1
	v_cndmask_b32_e32 v111, v167, v111, vcc
	v_cmp_lt_i32_e32 vcc, 25, v2
	s_nop 1
	v_cndmask_b32_e32 v112, v167, v112, vcc
	v_cmp_lt_i32_e32 vcc, 26, v2
	s_nop 1
	v_cndmask_b32_e32 v113, v167, v113, vcc
.Lmy_b_nomask0:
	s_waitcnt lgkmcnt(4)
	v_mfma_f32_32x32x16_bf16 v[82:97], v[190:193], v[130:133], v[82:97]
	v_exp_f32_e32 v2, v98
	v_exp_f32_e32 v4, v99
	v_exp_f32_e32 v5, v100
	v_exp_f32_e32 v6, v101
	v_add_f32_e32 v7, 0, v2
	v_mfma_f32_32x32x16_bf16 v[82:97], v[194:197], v[134:137], v[82:97]
	v_exp_f32_e32 v8, v102
	v_add_f32_e32 v7, v4, v7
	v_exp_f32_e32 v9, v103
	v_add_f32_e32 v7, v5, v7
	v_exp_f32_e32 v10, v104
	v_mfma_f32_32x32x16_bf16 v[82:97], v[198:201], v[138:141], v[82:97]
	v_add_f32_e32 v7, v6, v7
	v_exp_f32_e32 v11, v105
	v_add_f32_e32 v7, v8, v7
	v_exp_f32_e32 v16, v106
	v_add_f32_e32 v7, v9, v7
	v_mfma_f32_32x32x16_bf16 v[82:97], v[202:205], v[142:145], v[82:97]
	v_exp_f32_e32 v106, v107
	v_add_f32_e32 v7, v10, v7
	v_exp_f32_e32 v107, v108
	v_add_f32_e32 v7, v11, v7
	v_exp_f32_e32 v108, v109
	s_waitcnt lgkmcnt(0)
	v_mfma_f32_32x32x16_bf16 v[82:97], v[206:209], v[146:149], v[82:97]
	v_add_f32_e32 v7, v16, v7
	v_exp_f32_e32 v109, v110
	v_add_f32_e32 v7, v106, v7
	v_exp_f32_e32 v110, v111
	v_add_f32_e32 v7, v107, v7
	v_mfma_f32_32x32x16_bf16 v[82:97], v[210:213], v[154:157], v[82:97]
	v_exp_f32_e32 v111, v112
	v_add_f32_e32 v7, v108, v7
	v_exp_f32_e32 v112, v113
	v_add_f32_e32 v7, v109, v7
	v_add_f32_e32 v7, v110, v7
	v_mfma_f32_32x32x16_bf16 v[82:97], v[214:217], v[150:153], v[82:97]
	v_add_f32_e32 v7, v111, v7
	v_cvt_pk_bf16_f32 v4, v2, v4
	v_add_f32_e32 v17, v112, v7
	v_cvt_pk_bf16_f32 v5, v5, v6
	v_cvt_pk_bf16_f32 v6, v8, v9
	v_mfma_f32_32x32x16_bf16 v[82:97], v[218:221], v[158:161], v[82:97]
	v_cvt_pk_bf16_f32 v7, v10, v11
	v_cvt_pk_bf16_f32 v106, v16, v106
	v_cvt_pk_bf16_f32 v107, v107, v108
	v_cvt_pk_bf16_f32 v108, v109, v110
	v_cvt_pk_bf16_f32 v109, v111, v112
	s_lshl_b32 s89, s0, 14
	s_add_i32 s89, s89, 0x12000
	v_add_u32_e32 v2, s89, v163
	ds_read_b128 v[222:225], v2
	ds_read_b128 v[226:229], v2 offset:4096
	ds_read_b128 v[230:233], v2 offset:8192
	ds_read_b128 v[234:237], v2 offset:12288
	v_add_u32_e32 v2, s89, v171
	ds_read_b128 v[238:241], v2
	ds_read_b128 v[242:245], v2 offset:4096
	ds_read_b128 v[246:249], v2 offset:8192
	ds_read_b128 v[250:253], v2 offset:12288
	s_branch .LBB0_1016

; __device__ __forceinline__ void attn_unit(const Frame& F, int h, int qb, const float* qw, bool desc) {
;     ...
;         { const int tll = ATT_TILE(nt - 1); ATT_SMPV(tll, bp); }
.LBB0_1018:
	s_and_b32 s1, s33, 0x7f00
	s_cmp_gt_u32 s1, s70
	s_cbranch_scc1 .LBB0_1022
	s_or_b32 s33, s33, 63
	s_cmp_le_u32 s33, s44
	s_cbranch_scc1 .LBB0_1021
	v_add_u32_e32 v2, s44, v169
	v_lshl_add_u32 v16, v170, 2, s1
	v_sub_u32_e32 v2, v2, v16
	v_cmp_lt_i32_e32 vcc, 31, v2
	s_nop 1
	v_cndmask_b32_e32 v82, v167, v82, vcc
	v_cmp_lt_i32_e32 vcc, 32, v2
	s_nop 1
	v_cndmask_b32_e32 v83, v167, v83, vcc
	v_cmp_lt_i32_e32 vcc, 33, v2
	s_nop 1
	v_cndmask_b32_e32 v84, v167, v84, vcc
	v_cmp_lt_i32_e32 vcc, 34, v2
	s_nop 1
	v_cndmask_b32_e32 v85, v167, v85, vcc
	v_cmp_lt_i32_e32 vcc, 39, v2
	s_nop 1
	v_cndmask_b32_e32 v86, v167, v86, vcc
	v_cmp_lt_i32_e32 vcc, 40, v2
	s_nop 1
	v_cndmask_b32_e32 v87, v167, v87, vcc
	v_cmp_lt_i32_e32 vcc, 41, v2
	s_nop 1
	v_cndmask_b32_e32 v88, v167, v88, vcc
	v_cmp_lt_i32_e32 vcc, 42, v2
	s_nop 1
	v_cndmask_b32_e32 v89, v167, v89, vcc
	v_cmp_lt_i32_e32 vcc, 47, v2
	s_nop 1
	v_cndmask_b32_e32 v90, v167, v90, vcc
	v_cmp_lt_i32_e32 vcc, 48, v2
	s_nop 1
	v_cndmask_b32_e32 v91, v167, v91, vcc
	v_cmp_lt_i32_e32 vcc, 49, v2
	s_nop 1
	v_cndmask_b32_e32 v92, v167, v92, vcc
	v_cmp_lt_i32_e32 vcc, 50, v2
	s_nop 1
	v_cndmask_b32_e32 v93, v167, v93, vcc
	v_cmp_lt_i32_e32 vcc, 55, v2
	s_nop 1
	v_cndmask_b32_e32 v94, v167, v94, vcc
	v_cmp_lt_i32_e32 vcc, 56, v2
	s_nop 1
	v_cndmask_b32_e32 v95, v167, v95, vcc
	v_cmp_lt_i32_e32 vcc, 57, v2
	s_nop 1
	v_cndmask_b32_e32 v96, v167, v96, vcc
	v_cmp_lt_i32_e32 vcc, 58, v2
	s_nop 1
	v_cndmask_b32_e32 v97, v167, v97, vcc
.LBB0_1021:
	s_lshl_b32 s0, s0, 14
	s_add_i32 s0, s0, 0
	s_add_i32 s0, s0, 0x12000
	s_waitcnt lgkmcnt(7)
	v_mfma_f32_32x32x16_bf16 v[66:81], v[222:225], v[4:7], v[66:81]
	v_exp_f32_e32 v2, v82
	v_exp_f32_e32 v170, v83
	s_nop 0
	v_add_f32_e32 v195, v2, v170
	s_waitcnt lgkmcnt(6)
	v_mfma_f32_32x32x16_bf16 v[50:65], v[226:229], v[4:7], v[50:65]
	v_exp_f32_e32 v194, v84
	v_exp_f32_e32 v16, v85
	s_nop 0
	v_add_f32_e32 v8, v194, v16
	v_add_f32_e32 v9, v195, v17
	v_add_f32_e32 v197, v8, v9
	s_waitcnt lgkmcnt(5)
	v_mfma_f32_32x32x16_bf16 v[34:49], v[230:233], v[4:7], v[34:49]
	v_exp_f32_e32 v17, v86
	v_exp_f32_e32 v195, v87
	s_nop 0
	v_add_f32_e32 v199, v17, v195
	s_waitcnt lgkmcnt(4)
	v_mfma_f32_32x32x16_bf16 v[18:33], v[234:237], v[4:7], v[18:33]
	v_exp_f32_e32 v198, v88
	v_exp_f32_e32 v196, v89
	s_nop 0
	v_add_f32_e32 v8, v198, v196
	v_add_f32_e32 v9, v199, v197
	v_add_f32_e32 v201, v8, v9
	v_add_u32_e32 v82, s0, v181
	ds_read_b128 v[4:7], v82
	ds_read_b128 v[8:11], v82 offset:4096
	ds_read_b128 v[12:15], v82 offset:8192
	ds_read_b128 v[82:85], v82 offset:12288
	s_waitcnt lgkmcnt(7)
	v_mfma_f32_32x32x16_bf16 v[66:81], v[238:241], v[106:109], v[66:81]
	v_exp_f32_e32 v181, v90
	v_exp_f32_e32 v197, v91
	s_nop 0
	v_add_f32_e32 v203, v181, v197
	s_waitcnt lgkmcnt(6)
	v_mfma_f32_32x32x16_bf16 v[50:65], v[242:245], v[106:109], v[50:65]
	v_exp_f32_e32 v202, v92
	v_exp_f32_e32 v200, v93
	s_nop 0
	v_add_f32_e32 v86, v202, v200
	v_add_f32_e32 v87, v203, v201
	v_add_f32_e32 v111, v86, v87
	s_waitcnt lgkmcnt(5)
	v_mfma_f32_32x32x16_bf16 v[34:49], v[246:249], v[106:109], v[34:49]
	v_exp_f32_e32 v182, v94
	v_exp_f32_e32 v183, v95
	s_nop 0
	v_add_f32_e32 v113, v182, v183
	s_waitcnt lgkmcnt(4)
	v_mfma_f32_32x32x16_bf16 v[18:33], v[250:253], v[106:109], v[18:33]
	v_exp_f32_e32 v112, v96
	v_exp_f32_e32 v110, v97
	s_nop 0
	v_add_f32_e32 v86, v112, v110
	v_add_f32_e32 v87, v113, v111
	v_add_f32_e32 v102, v86, v87
	v_add_u32_e32 v98, s0, v180
	ds_read_b128 v[86:89], v98
	ds_read_b128 v[90:93], v98 offset:4096
	ds_read_b128 v[94:97], v98 offset:8192
	ds_read_b128 v[98:101], v98 offset:12288
	v_add_f32_e32 v178, v178, v102
	v_cvt_pk_bf16_f32 v102, v2, v170
	v_cvt_pk_bf16_f32 v103, v194, v16
	v_cvt_pk_bf16_f32 v104, v17, v195
	v_cvt_pk_bf16_f32 v105, v198, v196
	v_cvt_pk_bf16_f32 v106, v181, v197
	v_cvt_pk_bf16_f32 v107, v202, v200
	v_cvt_pk_bf16_f32 v108, v182, v183
	v_cvt_pk_bf16_f32 v109, v112, v110
	s_waitcnt lgkmcnt(7)
	v_mfma_f32_32x32x16_bf16 v[66:81], v[4:7], v[102:105], v[66:81]
	s_waitcnt lgkmcnt(6)
	v_mfma_f32_32x32x16_bf16 v[50:65], v[8:11], v[102:105], v[50:65]
	s_waitcnt lgkmcnt(5)
	v_mfma_f32_32x32x16_bf16 v[34:49], v[12:15], v[102:105], v[34:49]
	s_waitcnt lgkmcnt(4)
	v_mfma_f32_32x32x16_bf16 v[18:33], v[82:85], v[102:105], v[18:33]
	s_waitcnt lgkmcnt(0)
	v_mfma_f32_32x32x16_bf16 v[66:81], v[86:89], v[106:109], v[66:81]
	v_mfma_f32_32x32x16_bf16 v[50:65], v[90:93], v[106:109], v[50:65]
	v_mfma_f32_32x32x16_bf16 v[34:49], v[94:97], v[106:109], v[34:49]
	v_mfma_f32_32x32x16_bf16 v[18:33], v[98:101], v[106:109], v[18:33]
